# L2 warm-up reads for the second chunk-state unit of workgroups 0-31 (issued at the start of their first unit)
# baseline (speedup 1.0000x reference)
; __device__ __forceinline__ float log2_sigmoid(float x) { return -log1pf(expf(-x)) * 1.4426950408889634f; }
; __device__ __forceinline__ void state_unit(const bf16* __restrict__ Kc, const bf16* __restrict__ Vc, float* __restrict__ Sf, float* __restrict__ Sb, float lgf2, float lgb2, char* lds) {
;     ...
;         const bf16x8 a0 = *reinterpret_cast<const bf16x8*>(Vc + (size_t)(64 * t + sr) * 128 + sc), a1 = *reinterpret_cast<const bf16x8*>(Vc + (size_t)(64 * t + 32 + sr) * 128 + sc);
;         const bf16x8 k0 = *reinterpret_cast<const bf16x8*>(Kc + (size_t)(64 * t + kr) * 64 + kc);
; __global__ void __launch_bounds__(NTHR, 2) mega(Args args) {
;     ...
;         for (int idx = blockIdx.x; idx < 288; idx += G) {
;             const int b = idx & 7, rest = idx >> 3, h = rest / 9, c = rest % 9;
;             float* st = (float*)(ws + WS_ST) + ((size_t)((b * 4 + h) * 9 + c) * 2) * 8192;
;             ret::state_unit((const bf16*)(ws + WS_RK) + ((size_t)(b * 4 + h) * LT + 256 * c) * 64, (const bf16*)(ws + WS_RV) + ((size_t)(b * 4 + h) * LT + 256 * c) * 128,
;                             st, st + 8192, ret::log2_sigmoid(decay[h]), ret::log2_sigmoid(decay[4 + h]), (char*)lds_raw);
.LBB0_534:
	s_cmpk_gt_i32 s2, 0x11f
	s_cbranch_scc1 .LBB0_537
	s_cmp_gt_u32 s2, 31
	s_cbranch_scc1 .Ltouch2_skip
	s_add_i32 s66, s2, 0x100
	s_lshr_b32 s67, s66, 3
	s_and_b32 s66, s66, 7
	s_mul_i32 s68, s67, 57
	s_lshr_b32 s68, s68, 9
	s_mul_i32 s69, s68, 9
	s_sub_i32 s69, s67, s69
	s_lshl_b32 s66, s66, 2
	s_add_i32 s66, s66, s68
	s_mulk_i32 s66, 0x900
	s_lshl_b32 s69, s69, 8
	s_add_i32 s66, s66, s69
	s_lshl_b32 s67, s66, 7
	s_lshl_b32 s68, s66, 8
	s_add_u32 s70, s30, 0x7c00000
	s_addc_u32 s71, s31, 0
	s_add_u32 s70, s70, s67
	s_addc_u32 s71, s71, 0
	s_add_u32 s72, s30, 0x8500000
	s_addc_u32 s73, s31, 0
	s_add_u32 s72, s72, s68
	s_addc_u32 s73, s73, 0
	v_lshlrev_b32_e32 v236, 7, v0
	v_and_b32_e32 v237, 0x7f80, v236
	global_load_dword v238, v236, s[72:73]
	global_load_dword v237, v237, s[70:71]
.Ltouch2_skip:
	s_add_u32 s3, s30, 0xdb00000
	s_addc_u32 s12, s31, 0
	s_add_u32 s13, s30, 0x7c00000
	s_addc_u32 s14, s31, 0
	s_add_u32 s15, s30, 0x8500000
	s_addc_u32 s16, s31, 0
	s_lshl_b32 s17, s2, 2
	s_lshl_b32 s19, s18, 2
	v_mov_b32_e32 v35, 0
	s_mov_b32 s22, 0xbfb8aa3b
	s_mov_b32 s23, 0x42ce8ed0
	s_mov_b32 s34, 0xc2b17218
	s_mov_b32 s35, 0x7f800000
	v_mov_b32_e32 v1, 0x7f800000
	s_mov_b32 s40, 0x3f2aaaab
	v_mov_b32_e32 v62, 0x3ecc95a3
	s_mov_b32 s41, 0x3f317218
	s_mov_b32 s42, 0x33800000
	s_mov_b32 s43, 0xffff0000
	s_movk_i32 s46, 0x7fff
	s_movk_i32 s47, 0x4000
	s_movk_i32 s48, 0x6000
	s_mov_b32 s49, 0x8000
	s_mov_b32 s50, 0xa000
	s_mov_b32 s51, 0xc000
	s_mov_b32 s52, 0xe000
	v_mov_b32_e32 v63, 0x4000
	v_mov_b32_e32 v36, 0x3f317218
	s_add_i32 s53, 0, 0x10000
	s_add_i32 s58, 0, 0x18000
	s_mov_b32 s59, s2
